# v51 + mLSTM step 3: the six P.V fragments read up front into free registers
# speedup vs baseline: 1.0032x; 1.0032x over previous
; DI unsigned pk2(float a, float b) { f32x2 v = {a, b}; hbf2 r = __builtin_convertvector(v, hbf2); return __builtin_bit_cast(unsigned, r); }
; DI float bflo(unsigned u) { return __uint_as_float(u << 16); }
; DI float bfhi(unsigned u) { return __uint_as_float(u & 0xffff0000u); }
; DI float sum_x16_x32(float x) { return sum_x32(sum_x16(x)); }
; DI f32x4 mfma16(bf16x8 a, bf16x8 b, f32x4 c) { return __builtin_amdgcn_mfma_f32_16x16x32_bf16(a, b, c, 0, 0, 0); }
; DI void mlstm_unit(const Params& p, unsigned char* smem, int unit) {
;     ...
;         {
;             const int t = ti * 16 + fr;
;             const float wp = swp[t];
;             const float den = wp * snq[t] + (srs[t] + srs[64 + t]) + (srs[128 + t] + srs[192 + t]);
;             const float inv = __builtin_amdgcn_rcpf(fmaxf(fabsf(den), semt[t]));
;             const bool ok = t < nv && wr_out;
;             const size_t row = (size_t)(base + (ok ? t : 0));
;             float sq = 0.f;
; #pragma unroll
;             for (int x = 0; x < 2; ++x) {
;                 const int vi = pi + x;
;                 f32x4 a = accH[x] * wp;
; #pragma unroll
;                 for (int k2 = 0; k2 < 2; ++k2)
;                     a = mfma16(*(const bf16x8*)(sVt + (vi * 16 + fr) * 72 + k2 * 32 + fq * 8), *(const bf16x8*)(sSd + t * 72 + k2 * 32 + fq * 8), a);
;                 bf16_t* op = OG + row * 2048 + h * 256 + sl * 64 + vi * 16 + fq * 4;
;                 if (ok) {
;                     const u32x2 ov = x == 0 ? og0 : og1;
;                     const float h0 = a[0] * inv * bflo(ov.x), h1 = a[1] * inv * bfhi(ov.x), h2 = a[2] * inv * bflo(ov.y), h3 = a[3] * inv * bfhi(ov.y);
;                     u32x2 w; w.x = pk2(h0, h1); w.y = pk2(h2, h3);
;                     *(u32x2*)op = w;
;                     sq += h0 * h0 + h1 * h1 + h2 * h2 + h3 * h3;
;                 }
;             }
;             sq = sum_x16_x32(sq);
;             if (fq == 0 && ok) atomicAdd(HSS + row * 4 + h, sq);
;         }
.LBB0_399:
	s_or_b64 exec, exec, s[72:73]
	s_waitcnt lgkmcnt(0)
	s_barrier
	ds_read2st64_b32 v[90:91], v200 offset0:2 offset1:3
	ds_read_b32 v74, v156
	ds_read2st64_b32 v[72:73], v148 offset1:1
	s_cmp_lg_u32 s97, 0
	s_cselect_b64 s[72:73], -1, 0
	s_add_i32 s74, s86, s97
	s_sub_i32 s74, s74, 64
	s_waitcnt lgkmcnt(0)
	v_add_f32_e32 v75, v72, v73
	ds_read2st64_b32 v[72:73], v148 offset0:2 offset1:3
	s_or_b64 s[72:73], s[94:95], s[72:73]
	s_cmp_eq_u32 s97, 0
	s_cselect_b32 s75, 16, 64
	v_fmac_f32_e32 v75, v90, v74
	s_waitcnt lgkmcnt(0)
	v_add_f32_e32 v72, v72, v73
	v_add_f32_e32 v72, v75, v72
	v_max_f32_e32 v73, v91, v91
	v_cmp_gt_i32_e32 vcc, s75, v144
	s_cselect_b32 s74, 0x8000, s74
	v_max_f32_e64 v72, |v72|, v73
	s_and_b64 vcc, s[72:73], vcc
	v_rcp_f32_e32 v86, v72
	v_cndmask_b32_e32 v72, 0, v144, vcc
	ds_read_b128 v[80:83], v194
	ds_read_b128 v[76:79], v195
	ds_read_b128 v[92:95], v194 offset:64
	ds_read_b128 v[212:215], v195 offset:64
	ds_read_b128 v[216:219], v196
	ds_read_b128 v[220:223], v196 offset:64
	v_add_u32_e32 v84, s74, v72
	v_ashrrev_i32_e32 v85, 31, v84
	v_lshlrev_b64 v[72:73], 12, v[84:85]
	v_lshl_add_u64 v[88:89], v[108:109], 0, v[72:73]
	v_pk_mul_f32 v[74:75], v[102:103], v[90:91] op_sel_hi:[1,0]
	v_pk_mul_f32 v[72:73], v[100:101], v[90:91] op_sel_hi:[1,0]
	v_mov_b32_e32 v87, 0
	s_waitcnt lgkmcnt(4)
	v_mfma_f32_16x16x32_bf16 v[80:83], v[80:83], v[76:79], v[72:75]
	s_waitcnt lgkmcnt(2)
	v_mfma_f32_16x16x32_bf16 v[80:83], v[92:95], v[212:215], v[80:83]
	s_and_saveexec_b64 s[72:73], vcc
	s_cbranch_execz .LBB0_401
	s_nop 5
	v_pk_mul_f32 v[80:81], v[86:87], v[80:81] op_sel_hi:[0,1]
	s_waitcnt vmcnt(12)
	v_lshlrev_b32_e32 v94, 16, v132
	v_and_b32_e32 v95, 0xffff0000, v132
	v_pk_mul_f32 v[80:81], v[80:81], v[94:95]
	v_pk_mul_f32 v[82:83], v[86:87], v[82:83] op_sel_hi:[0,1]
	v_and_b32_e32 v97, 0xffff0000, v133
	v_lshlrev_b32_e32 v96, 16, v133
	v_cvt_pk_bf16_f32 v94, v80, v81
	v_pk_mul_f32 v[80:81], v[80:81], v[80:81]
	v_pk_mul_f32 v[82:83], v[82:83], v[96:97]
	v_add_f32_e32 v80, v80, v81
	v_cvt_pk_bf16_f32 v95, v82, v83
	v_pk_mul_f32 v[82:83], v[82:83], v[82:83]
	v_lshl_add_u64 v[92:93], v[88:89], 0, v[104:105]
	v_add_f32_e32 v80, v82, v80
	v_add_f32_e32 v87, v83, v80
	global_store_dwordx2 v[92:93], v[94:95], off
.LBB0_401:
	s_or_b64 exec, exec, s[72:73]
	s_nop 4
	v_mov_b32_e32 v80, v90
	v_mov_b32_e32 v81, v90
	v_pk_mul_f32 v[70:71], v[70:71], v[80:81]
	v_mov_b32_e32 v91, v90
	v_pk_mul_f32 v[68:69], v[68:69], v[90:91]
	s_waitcnt lgkmcnt(0)
	s_nop 0
	v_mfma_f32_16x16x32_bf16 v[68:71], v[216:219], v[76:79], v[68:71]
	v_mfma_f32_16x16x32_bf16 v[68:71], v[220:223], v[212:215], v[68:71]
	s_and_saveexec_b64 s[72:73], vcc
	s_cbranch_execz .LBB0_403
	s_nop 5
	v_pk_mul_f32 v[68:69], v[86:87], v[68:69] op_sel_hi:[0,1]
	s_waitcnt vmcnt(11)
	v_lshlrev_b32_e32 v74, 16, v130
	v_and_b32_e32 v75, 0xffff0000, v130
	v_pk_mul_f32 v[68:69], v[68:69], v[74:75]
	v_pk_mul_f32 v[70:71], v[86:87], v[70:71] op_sel_hi:[0,1]
	v_and_b32_e32 v77, 0xffff0000, v131
	v_lshlrev_b32_e32 v76, 16, v131
	v_cvt_pk_bf16_f32 v74, v68, v69
	v_pk_mul_f32 v[68:69], v[68:69], v[68:69]
	v_pk_mul_f32 v[70:71], v[70:71], v[76:77]
	v_add_f32_e32 v68, v68, v69
	v_cvt_pk_bf16_f32 v75, v70, v71
	v_pk_mul_f32 v[70:71], v[70:71], v[70:71]
	v_lshlrev_b32_e32 v72, 1, v118
	v_add_f32_e32 v68, v70, v68
	v_mov_b32_e32 v73, v105
	v_add_f32_e32 v68, v71, v68
	v_lshl_add_u64 v[72:73], v[88:89], 0, v[72:73]
	v_add_f32_e32 v87, v87, v68
	global_store_dwordx2 v[72:73], v[74:75], off
